# in-proj tile grouping GM=8 (8x8 XCD patch) instead of GM=4
# baseline (speedup 1.0000x reference)
; template <int EPI>
; __device__ __forceinline__ void gemm_tile(const bf16_t* __restrict__ A, const int lda, const bf16_t* __restrict__ Bt, const int ldb,
;                                           const int K, const int m0, const int n0, void* Cout, const int ldc, char* lds, const int tid) {
;     ...
;   f32x4 acc[4][4];
; #pragma unroll
;   for (int m = 0; m < 4; ++m)
; #pragma unroll
;     for (int n = 0; n < 4; ++n) acc[m][n] = (f32x4){0.f, 0.f, 0.f, 0.f};
;   const int nt = K >> 6;
;   const int st_row = tid >> 3, st_c = (tid & 7) ^ ((tid >> 4) & 7);
;   auto stageA = [&](int kt, int buf) {
; #pragma unroll
;     for (int i = 0; i < 4; ++i) {
;       const int off = tid * 16 + i * 4096, r = st_row + i * 32;
;       const bf16_t* ga = A + (size_t)(m0 + r) * lda + kt * 64 + st_c * 8;
;       __builtin_amdgcn_global_load_lds((const unsigned*)ga, (__attribute__((address_space(3))) unsigned*)(lds + buf * 32768 + off), 16, 0, 0);
;     }
;   };
;   auto stageB = [&](int kt, int buf) {
; #pragma unroll
;     for (int i = 0; i < 4; ++i) {
;       const int off = tid * 16 + i * 4096, r = st_row + i * 32;
;       const bf16_t* gb = Bt + (size_t)(n0 + r) * ldb + kt * 64 + st_c * 8;
;       __builtin_amdgcn_global_load_lds((const unsigned*)gb, (__attribute__((address_space(3))) unsigned*)(lds + buf * 32768 + 16384 + off), 16, 0, 0);
;     }
;   };
;   auto stage = [&](int kt, int buf) { stageA(kt, buf); stageB(kt, buf); };
;   const int fsw = (fr >> 1) & 7;
;   const int xk0 = (fq ^ fsw) << 4, xk1 = ((4 + fq) ^ fsw) << 4;
;   stage(0, 0);
; template <int EPI>
; __device__ __forceinline__ void gemm_phase(const bf16_t* A, int lda, const bf16_t* Bt, int ldb, int K, int ntn, void* C, int ldc, char* lds, int bid, int nb, const int tid) {
;   constexpr int GM = 4, nM = MT / 128;
;   const int ntiles = nM * ntn, nig = GM * ntn;
;   const int pos = (EPI != EPI_SWIGLU && (nb & 7) == 0) ? (bid & 7) * (nb >> 3) + (bid >> 3) : bid;
;   for (int L = pos; L < ntiles; L += nb) {
;     int mt, nn;
;     if (EPI == EPI_SWIGLU) { mt = L / ntn; nn = L % ntn; }
;     else { const int gid = L / nig, fm = gid * GM, gsz = min(nM - fm, GM), rem = L - gid * nig; mt = fm + rem % gsz; nn = rem / gsz; }
;     gemm_tile<EPI>(A, lda, Bt, ldb, K, mt * 128, nn * 128, C, ldc, lds, tid);
.LBB0_648:
	s_mul_hi_i32 s2, s23, 0x84210843
	s_add_i32 s2, s2, s23
	s_lshr_b32 s3, s2, 31
	s_ashr_i32 s2, s2, 7
	s_add_i32 s2, s2, s3
	s_lshl_b32 s3, s2, 3
	s_sub_i32 s24, 0x85, s3
	s_min_u32 s24, s24, 8
	v_cvt_f32_ubyte0_e32 v2, s24
	v_rcp_iflag_f32_e32 v2, v2
	s_sub_i32 s27, 0, s24
	s_mulk_i32 s2, 0xff08
	s_add_i32 s2, s2, s23
	v_mul_f32_e32 v2, 0x4f7ffffe, v2
	v_cvt_u32_f32_e32 v2, v2
	s_abs_i32 s26, s2
	s_ashr_i32 s25, s2, 31
	v_readfirstlane_b32 s29, v2
	s_mul_i32 s27, s27, s29
	s_mul_hi_u32 s27, s29, s27
	s_add_i32 s29, s29, s27
	s_mul_hi_u32 s27, s26, s29
	s_mul_i32 s29, s27, s24
	s_sub_i32 s26, s26, s29
	s_add_i32 s29, s27, 1
	s_sub_i32 s34, s26, s24
	s_cmp_ge_u32 s26, s24
	s_cselect_b32 s27, s29, s27
	s_cselect_b32 s26, s34, s26
	s_add_i32 s29, s27, 1
	s_cmp_ge_u32 s26, s24
	s_cselect_b32 s26, s29, s27
	s_xor_b32 s26, s26, s25
	s_sub_i32 s25, s26, s25
	s_mul_i32 s24, s25, s24
	s_sub_i32 s2, s2, s24
	s_add_i32 s3, s3, s2
	s_lshl_b32 s3, s3, 7
	v_add_u32_e32 v4, s3, v174
	v_ashrrev_i32_e32 v5, 31, v4
	v_lshlrev_b64 v[4:5], 11, v[4:5]
	v_readfirstlane_b32 s24, v177
	v_lshl_add_u64 v[6:7], v[0:1], 0, v[4:5]
	s_mov_b32 m0, s24
	v_add_u32_e32 v2, 0x1000, v177
	global_load_lds_dwordx4 v[6:7], off
	v_add_u32_e32 v6, s3, v178
	v_ashrrev_i32_e32 v7, 31, v6
	v_lshlrev_b64 v[6:7], 11, v[6:7]
	v_readfirstlane_b32 s24, v2
	v_lshl_add_u64 v[8:9], v[0:1], 0, v[6:7]
	s_mov_b32 m0, s24
	v_add_u32_e32 v2, 0x2000, v177
	global_load_lds_dwordx4 v[8:9], off
	v_add_u32_e32 v8, s3, v179
	v_ashrrev_i32_e32 v9, 31, v8
	v_lshlrev_b64 v[8:9], 11, v[8:9]
	v_readfirstlane_b32 s24, v2
	v_lshl_add_u64 v[10:11], v[0:1], 0, v[8:9]
	s_mov_b32 m0, s24
	v_add_u32_e32 v2, 0x3000, v177
	global_load_lds_dwordx4 v[10:11], off
	v_add_u32_e32 v10, s3, v180
	v_ashrrev_i32_e32 v11, 31, v10
	v_lshlrev_b64 v[10:11], 11, v[10:11]
	v_readfirstlane_b32 s24, v2
	s_lshl_b32 s2, s25, 7
	v_lshl_add_u64 v[12:13], v[0:1], 0, v[10:11]
	s_mov_b32 m0, s24
	v_add_u32_e32 v2, 0x4000, v177
	global_load_lds_dwordx4 v[12:13], off
	v_add_u32_e32 v12, s2, v174
	v_ashrrev_i32_e32 v13, 31, v12
	v_lshlrev_b64 v[12:13], 11, v[12:13]
	v_readfirstlane_b32 s24, v2
	v_lshl_add_u64 v[14:15], v[132:133], 0, v[12:13]
	s_mov_b32 m0, s24
	v_add_u32_e32 v2, 0x5000, v177
	global_load_lds_dwordx4 v[14:15], off
	v_add_u32_e32 v14, s2, v178
	v_ashrrev_i32_e32 v15, 31, v14
	v_lshlrev_b64 v[14:15], 11, v[14:15]
	v_readfirstlane_b32 s24, v2
	v_lshl_add_u64 v[16:17], v[132:133], 0, v[14:15]
	s_mov_b32 m0, s24
	v_add_u32_e32 v2, 0x6000, v177
	global_load_lds_dwordx4 v[16:17], off
	v_add_u32_e32 v16, s2, v179
	v_ashrrev_i32_e32 v17, 31, v16
	v_lshlrev_b64 v[16:17], 11, v[16:17]
	v_readfirstlane_b32 s24, v2
	v_lshl_add_u64 v[18:19], v[132:133], 0, v[16:17]
	s_mov_b32 m0, s24
	v_add_u32_e32 v2, 0x7000, v177
	global_load_lds_dwordx4 v[18:19], off
	v_add_u32_e32 v18, s2, v180
	v_ashrrev_i32_e32 v19, 31, v18
	v_lshlrev_b64 v[18:19], 11, v[18:19]
	v_readfirstlane_b32 s24, v2
	v_lshl_add_u64 v[20:21], v[132:133], 0, v[18:19]
	s_mov_b32 m0, s24
	v_lshl_add_u64 v[148:149], v[138:139], 0, v[4:5]
	global_load_lds_dwordx4 v[20:21], off
	v_mov_b32_e32 v4, 0
	s_mov_b32 s25, 0
	v_lshl_add_u64 v[140:141], v[136:137], 0, v[12:13]
	v_lshl_add_u64 v[142:143], v[136:137], 0, v[14:15]
	v_lshl_add_u64 v[144:145], v[136:137], 0, v[16:17]
	v_lshl_add_u64 v[146:147], v[136:137], 0, v[18:19]
	v_lshl_add_u64 v[150:151], v[138:139], 0, v[6:7]
	v_lshl_add_u64 v[152:153], v[138:139], 0, v[8:9]
	v_lshl_add_u64 v[154:155], v[138:139], 0, v[10:11]
	s_mov_b64 s[34:35], 0
	v_mov_b32_e32 v5, v4
	v_mov_b32_e32 v6, v4
	v_mov_b32_e32 v7, v4
	v_mov_b32_e32 v16, v4
	v_mov_b32_e32 v17, v4
	v_mov_b32_e32 v18, v4
	v_mov_b32_e32 v19, v4
	v_mov_b32_e32 v40, v4
	v_mov_b32_e32 v41, v4
	v_mov_b32_e32 v42, v4
	v_mov_b32_e32 v43, v4
	v_mov_b32_e32 v48, v4
	v_mov_b32_e32 v49, v4
	v_mov_b32_e32 v50, v4
	v_mov_b32_e32 v51, v4
	v_mov_b32_e32 v52, v4
	v_mov_b32_e32 v53, v4
	v_mov_b32_e32 v54, v4
	v_mov_b32_e32 v55, v4
	v_mov_b32_e32 v32, v4
	v_mov_b32_e32 v33, v4
	v_mov_b32_e32 v34, v4
	v_mov_b32_e32 v35, v4
	v_mov_b32_e32 v20, v4
	v_mov_b32_e32 v21, v4
	v_mov_b32_e32 v22, v4
	v_mov_b32_e32 v23, v4
	v_mov_b32_e32 v8, v4
	v_mov_b32_e32 v9, v4
	v_mov_b32_e32 v10, v4
	v_mov_b32_e32 v11, v4
	v_mov_b32_e32 v24, v4
	v_mov_b32_e32 v25, v4
	v_mov_b32_e32 v26, v4
	v_mov_b32_e32 v27, v4
	v_mov_b32_e32 v12, v4
	v_mov_b32_e32 v13, v4
	v_mov_b32_e32 v14, v4
	v_mov_b32_e32 v15, v4
	v_mov_b32_e32 v28, v4
	v_mov_b32_e32 v29, v4
	v_mov_b32_e32 v30, v4
	v_mov_b32_e32 v31, v4
	v_mov_b32_e32 v36, v4
	v_mov_b32_e32 v37, v4
	v_mov_b32_e32 v38, v4
	v_mov_b32_e32 v39, v4
	v_mov_b32_e32 v44, v4
	v_mov_b32_e32 v45, v4
	v_mov_b32_e32 v46, v4
	v_mov_b32_e32 v47, v4
	v_mov_b32_e32 v56, v4
	v_mov_b32_e32 v57, v4
	v_mov_b32_e32 v58, v4
	v_mov_b32_e32 v59, v4
	v_mov_b32_e32 v60, v4
	v_mov_b32_e32 v61, v4
	v_mov_b32_e32 v62, v4
	v_mov_b32_e32 v63, v4
	v_mov_b32_e32 v64, v4
	v_mov_b32_e32 v65, v4
	v_mov_b32_e32 v66, v4
	v_mov_b32_e32 v67, v4
